# plus F1 per-token loads prefetched one token ahead; SwiGLU GEMM epilogue rewritten with packed f32 ops (same per-element arithmetic)
# speedup vs baseline: 1.0230x; 1.0125x over previous
; __global__ void __launch_bounds__(512, 2) fwd_mega(Args args) {
;     ...
;                 { const float* gsrc = (hh < 6 ? ap->in[12] : ap->in[13]) + l * 64 + dim0;
;                   const float* gcq = ap->in[16] + l * 384; const float* gckv = ap->in[17] + l * 256; const float* gkr = ap->in[23] + l * 32 + (lane & 3) * 8;
;                   const float* cw = ap->in[14] + l * 3 * 256 + 4 * lane; const float* cb = ap->in[15] + l * 256 + 4 * lane;
; #pragma unroll
;                   for (int e = 0; e < 8; ++e) { g8[e] = gsrc[e] * (hh < 6 ? QSCALE_A : 1.0f); inv8[e] = rope_inv64((lane & 1) * 8 + e); ik8[e] = rope_inv32(e); gkr8[e] = gkr[e];
;                       gc0[e] = lane < 48 ? gcq[8 * lane + e] : gckv[8 * (lane - 48) + e]; gc1[e] = gckv[128 + 8 * (lane & 15) + e]; }
; #pragma unroll
;                   for (int i = 0; i < 4; ++i) { cw0[i] = cw[i]; cw1[i] = cw[256 + i]; cw2[i] = cw[512 + i]; cb4[i] = cb[i]; } }
;     ...
;                 for (int r = gw; r < MTOT; r += NGW) {
;                     const bool lat = r < MLAT; int b, s;
;                     if (lat) { b = r >> 11; s = r & 2047; } else { b = (r - MLAT) >> 8; s = (r - MLAT) & 255; }
;                     const int pos = lat ? CTXL + s : s, smax = lat ? SEQ - 1 : CTXL - 1;
;                     const float prow = (float)(s >> 6), pcol = (float)(s & 63);
;                     const GAS bf16* p = P + (size_t)r * INP;
;                     const u32x4 a8 = *(const GAS u32x4*)(p + 8 * lane);
;                     const u32x4 v8 = *(const GAS u32x4*)(p + PC_V + 8 * (lane & 15));
;                     const u32x4 c0 = *(const GAS u32x4*)(p + PC_CQ + 8 * lane);
;                     const u32x4 c1 = *(const GAS u32x4*)(p + PC_CQ + 512 + 8 * (lane & 15));
;                     const u32x4 k8 = *(const GAS u32x4*)(p + PC_KR + 8 * (lane & 3));
;                     const u32x2 xi = *(const GAS u32x2*)(p + PC_X + 4 * lane), cg = *(const GAS u32x2*)(p + PC_CG + 4 * lane), bg = *(const GAS u32x2*)(p + PC_BG + 4 * lane);
;                     u32x2 xm = (u32x2){0u, 0u}, cm = xm, xp = xm, cp = xm;
;                     if (s > 0) { xm = *(const GAS u32x2*)(p - INP + PC_X + 4 * lane); cm = *(const GAS u32x2*)(p - INP + PC_CG + 4 * lane); }
;                     if (s < smax) { xp = *(const GAS u32x2*)(p + INP + PC_X + 4 * lane); cp = *(const GAS u32x2*)(p + INP + PC_CG + 4 * lane); }
.LBB0_187:
	v_lshlrev_b32_e32 v0, 3, v27
	s_mul_i32 s4, s26, 0x300
	s_ashr_i32 s5, s4, 31
	v_lshlrev_b32_e32 v0, 1, v0
	s_waitcnt vmcnt(0) lgkmcnt(0)
	v_lshl_add_u64 v[2:3], s[4:5], 2, v[2:3]
	v_lshl_add_u64 v[36:37], s[34:35], 0, v[0:1]
	s_mov_b64 s[4:5], 0x18d00000
	v_lshl_add_u64 v[64:65], v[36:37], 0, s[4:5]
	v_lshlrev_b32_e32 v36, 1, v18
	v_and_b32_e32 v37, 16, v36
	v_or_b32_e32 v36, 14, v37
	v_cvt_f32_ubyte0_e32 v36, v36
	v_mul_f32_e32 v39, 0xbed49a78, v36
	s_mov_b32 s4, 0xc2fc0000
	v_cmp_gt_f32_e64 s[44:45], s4, v39
	v_or_b32_e32 v61, 10, v37
	v_cvt_f32_ubyte0_e32 v61, v61
	v_cndmask_b32_e64 v39, 0, v225, s[44:45]
	v_fmac_f32_e32 v39, 0xbed49a78, v36
	v_exp_f32_e32 v39, v39
	v_cndmask_b32_e32 v36, 1.0, v224, vcc
	v_mul_f32_e32 v66, v36, v32
	v_or_b32_e32 v32, 12, v37
	v_mul_f32_e32 v67, v36, v33
	v_cndmask_b32_e64 v33, 0, v247, s[44:45]
	v_cvt_f32_ubyte0_e32 v32, v32
	v_ldexp_f32 v39, v39, v33
	v_mul_f32_e32 v33, 0xbed49a78, v32
	v_cmp_gt_f32_e32 vcc, s4, v33
	v_mul_f32_e32 v63, 0xbed49a78, v61
	v_lshlrev_b32_e32 v34, 2, v198
	v_cndmask_b32_e32 v33, 0, v225, vcc
	v_fmac_f32_e32 v33, 0xbed49a78, v32
	v_exp_f32_e32 v32, v33
	v_cndmask_b32_e32 v33, 0, v247, vcc
	v_cmp_gt_f32_e32 vcc, s4, v63
	v_ashrrev_i32_e32 v35, 31, v34
	v_lshl_add_u64 v[4:5], s[22:23], 2, v[4:5]
	v_cndmask_b32_e32 v63, 0, v225, vcc
	v_fmac_f32_e32 v63, 0xbed49a78, v61
	v_lshlrev_b64 v[6:7], 2, v[34:35]
	v_exp_f32_e32 v61, v63
	v_lshl_add_u64 v[10:11], v[2:3], 0, v[6:7]
	v_lshl_add_u64 v[14:15], v[4:5], 0, v[6:7]
	flat_load_dwordx4 v[2:5], v[10:11]
	flat_load_dwordx4 v[6:9], v[10:11] offset:1024
	s_nop 0
	flat_load_dwordx4 v[10:13], v[10:11] offset:2048
	s_nop 0
	flat_load_dwordx4 v[14:17], v[14:15]
	v_mul_f32_e32 v69, v36, v31
	v_cndmask_b32_e32 v31, 0, v247, vcc
	v_ldexp_f32 v112, v61, v31
	flat_load_dword v63, v[22:23] offset:540
	flat_load_dword v61, v[24:25]
	v_mul_f32_e32 v68, v36, v30
	v_or_b32_e32 v30, 8, v37
	v_cvt_f32_ubyte0_e32 v30, v30
	v_mul_f32_e32 v31, 0xbed49a78, v30
	v_ldexp_f32 v75, v32, v33
	v_cmp_gt_f32_e32 vcc, s4, v31
	v_or_b32_e32 v32, 6, v37
	v_cvt_f32_ubyte0_e32 v32, v32
	v_cndmask_b32_e32 v31, 0, v225, vcc
	v_fmac_f32_e32 v31, 0xbed49a78, v30
	v_mul_f32_e32 v33, 0xbed49a78, v32
	v_exp_f32_e32 v30, v31
	v_cndmask_b32_e32 v31, 0, v247, vcc
	v_cmp_gt_f32_e32 vcc, s4, v33
	v_mul_f32_e32 v71, v36, v29
	v_ldexp_f32 v113, v30, v31
	v_cndmask_b32_e32 v33, 0, v225, vcc
	v_fmac_f32_e32 v33, 0xbed49a78, v32
	v_exp_f32_e32 v32, v33
	v_cndmask_b32_e32 v29, 0, v247, vcc
	v_or_b32_e32 v24, 2, v37
	v_cvt_f32_ubyte0_e32 v24, v24
	v_ldexp_f32 v114, v32, v29
	v_or_b32_e32 v29, 4, v37
	v_cvt_f32_ubyte0_e32 v29, v29
	v_mul_f32_e32 v30, 0xbed49a78, v29
	v_cmp_gt_f32_e32 vcc, s4, v30
	v_mul_f32_e32 v25, 0xbed49a78, v24
	v_pk_mul_f32 v[72:73], v[36:37], v[20:21] op_sel_hi:[0,1]
	v_cndmask_b32_e32 v30, 0, v225, vcc
	v_fmac_f32_e32 v30, 0xbed49a78, v29
	v_exp_f32_e32 v29, v30
	v_cndmask_b32_e32 v22, 0, v247, vcc
	s_add_u32 s22, s34, 0x17b00000
	v_lshlrev_b32_e32 v76, 3, v26
	v_ldexp_f32 v115, v29, v22
	v_cvt_f32_ubyte0_e32 v22, v37
	v_mul_f32_e32 v23, 0xbed49a78, v22
	v_cmp_gt_f32_e32 vcc, s4, v23
	s_addc_u32 s23, s35, 0
	s_add_u32 s60, s34, 0x18880000
	v_cndmask_b32_e32 v23, 0, v225, vcc
	v_fmac_f32_e32 v23, 0xbed49a78, v22
	v_exp_f32_e32 v22, v23
	v_cndmask_b32_e32 v23, 0, v247, vcc
	v_cmp_gt_f32_e32 vcc, s4, v25
	v_mov_b32_e32 v21, v1
	s_addc_u32 s61, s35, 0
	v_cndmask_b32_e32 v25, 0, v225, vcc
	v_fmac_f32_e32 v25, 0xbed49a78, v24
	v_exp_f32_e32 v24, v25
	v_cndmask_b32_e32 v20, 0, v247, vcc
	s_mov_b64 s[4:5], 0x1a5c0000
	s_mov_b32 s6, s21
	v_ldexp_f32 v117, v24, v20
	v_and_b32_e32 v20, 2, v198
	v_cmp_eq_u32_e64 s[46:47], 0, v20
	v_and_b32_e32 v20, 1, v198
	v_cmp_eq_u32_e64 s[52:53], 0, v20
	v_lshlrev_b32_e32 v20, 1, v76
	v_lshl_add_u64 v[20:21], s[34:35], 0, v[20:21]
	s_ashr_i32 s21, s20, 31
	v_lshl_add_u64 v[76:77], v[20:21], 0, s[4:5]
	s_lshl_b64 s[4:5], s[20:21], 11
	s_add_u32 s4, s34, s4
	v_lshlrev_b64 v[78:79], 1, v[34:35]
	s_addc_u32 s5, s35, s5
	v_lshl_add_u64 v[20:21], s[4:5], 0, v[78:79]
	s_mov_b64 s[4:5], 0x1c780300
	v_lshl_add_u64 v[80:81], v[20:21], 0, s[4:5]
	s_ashr_i32 s37, s36, 31
	v_lshlrev_b64 v[18:19], 1, v[18:19]
	s_mov_b64 s[4:5], 0xb00
	s_lshl_b64 s[70:71], s[36:37], 11
	v_lshl_add_u64 v[82:83], v[18:19], 0, s[4:5]
	s_mul_i32 s5, s20, 0x1200
	s_mul_hi_i32 s4, s20, 0x1200
	s_add_u32 s5, s34, s5
	s_addc_u32 s4, s35, s4
	s_add_u32 s72, s5, 0x11380000
	s_addc_u32 s73, s4, 0
	s_mul_i32 s4, s20, 0x500
	s_mul_hi_i32 s5, s20, 0x500
	s_add_u32 s4, s34, s4
	s_addc_u32 s5, s35, s5
	v_lshl_add_u64 v[18:19], s[4:5], 0, v[18:19]
	s_mov_b64 s[4:5], 0x16480400
	v_lshl_add_u64 v[84:85], v[18:19], 0, s[4:5]
	v_and_b32_e32 v18, 15, v198
	v_mul_f32_e32 v70, v36, v28
	v_ldexp_f32 v116, v22, v23
	v_cmp_gt_u32_e64 s[44:45], 4, v27
	v_add_u32_e32 v118, -6, v38
	v_cmp_gt_i32_e64 s[48:49], 16, v198
	v_cmp_gt_u32_e64 s[50:51], 2, v26
	v_cmp_gt_i32_e64 s[54:55], 24, v198
	v_ashrrev_i32_e32 v74, 2, v198
	v_xor_b32_e32 v119, 4, v34
	v_xor_b32_e32 v120, 8, v34
	v_xor_b32_e32 v121, 16, v34
	v_xor_b32_e32 v122, 32, v34
	v_xor_b32_e32 v123, 64, v34
	v_xor_b32_e32 v124, 0x80, v34
	v_cmp_lt_i32_e64 s[56:57], 47, v198
	s_mov_b32 s21, s6
	s_mul_hi_i32 s65, s36, 0x500
	s_mul_i32 s64, s36, 0x500
	v_lshl_or_b32 v86, v26, 4, v248
	v_mov_b32_e32 v87, v1
	v_lshlrev_b32_e32 v88, 4, v18
	v_mov_b32_e32 v89, v1
	s_mov_b32 s4, s20
	v_lshl_add_u64 v[176:177], s[72:73], 0, v[82:83]
	v_lshl_add_u64 v[178:179], s[72:73], 0, v[88:89]
	global_load_dwordx4 v[158:161], v[176:177], off offset:-2816
	global_load_dwordx4 v[142:145], v[176:177], off
	global_load_dwordx4 v[154:157], v[178:179], off offset:1024
	global_load_dwordx4 v[146:149], v[178:179], off offset:3840
	v_lshl_add_u64 v[180:181], s[72:73], 0, v[86:87]
	v_lshl_add_u64 v[182:183], s[72:73], 0, v[78:79]
	global_load_dwordx4 v[150:153], v[180:181], off
	global_load_dwordx2 v[164:165], v[182:183], off offset:1280
	global_load_dwordx2 v[166:167], v[182:183], off offset:2304
	global_load_dwordx2 v[162:163], v[182:183], off offset:1792
	s_cmpk_lt_i32 s4, 0x4000
	s_cselect_b32 s14, s90, 0xff
	s_and_b32 s11, s4, s14
	s_cmp_eq_u32 s11, 0
	s_cbranch_scc1 .Lf1p_prev_zero
	global_load_dwordx2 v[168:169], v[182:183], off offset:-3328
	global_load_dwordx2 v[170:171], v[182:183], off offset:-2304
	s_branch .Lf1p_prev_done
.Lf1p_prev_zero:
	v_mov_b32_e32 v168, 0
	v_mov_b32_e32 v169, 0
	v_mov_b32_e32 v170, 0
	v_mov_b32_e32 v171, 0
.Lf1p_prev_done:
	v_mov_b32_e32 v172, 0
	v_mov_b32_e32 v173, 0
	v_mov_b32_e32 v174, 0
	v_mov_b32_e32 v175, 0
	s_cmp_ge_u32 s11, s14
	s_cbranch_scc1 .Lf1p_next_done
	v_add_co_u32_e32 v184, vcc, 0x1000, v182
	s_nop 1
	v_addc_co_u32_e32 v185, vcc, 0, v183, vcc
	global_load_dwordx2 v[172:173], v[184:185], off offset:1792
	global_load_dwordx2 v[174:175], v[184:185], off offset:2816
.Lf1p_next_done:
	s_waitcnt vmcnt(0)
	s_branch .LBB0_189

; #define GAS __attribute__((address_space(1)))
; __global__ void __launch_bounds__(512, 2) fwd_mega(Args args) {
;     ...
;                 for (int r = gw; r < MTOT; r += NGW) {
;                     const bool lat = r < MLAT; int b, s;
;                     if (lat) { b = r >> 11; s = r & 2047; } else { b = (r - MLAT) >> 8; s = (r - MLAT) & 255; }
;                     const int pos = lat ? CTXL + s : s, smax = lat ? SEQ - 1 : CTXL - 1;
;                     const float prow = (float)(s >> 6), pcol = (float)(s & 63);
;                     const GAS bf16* p = P + (size_t)r * INP;
;                     const u32x4 a8 = *(const GAS u32x4*)(p + 8 * lane);
;                     const u32x4 v8 = *(const GAS u32x4*)(p + PC_V + 8 * (lane & 15));
;                     const u32x4 c0 = *(const GAS u32x4*)(p + PC_CQ + 8 * lane);
;                     const u32x4 c1 = *(const GAS u32x4*)(p + PC_CQ + 512 + 8 * (lane & 15));
;                     const u32x4 k8 = *(const GAS u32x4*)(p + PC_KR + 8 * (lane & 3));
;                     const u32x2 xi = *(const GAS u32x2*)(p + PC_X + 4 * lane), cg = *(const GAS u32x2*)(p + PC_CG + 4 * lane), bg = *(const GAS u32x2*)(p + PC_BG + 4 * lane);
;                     u32x2 xm = (u32x2){0u, 0u}, cm = xm, xp = xm, cp = xm;
;                     if (s > 0) { xm = *(const GAS u32x2*)(p - INP + PC_X + 4 * lane); cm = *(const GAS u32x2*)(p - INP + PC_CG + 4 * lane); }
;                     if (s < smax) { xp = *(const GAS u32x2*)(p + INP + PC_X + 4 * lane); cp = *(const GAS u32x2*)(p + INP + PC_CG + 4 * lane); }
.LBB0_189:
	s_waitcnt vmcnt(3)
	v_mov_b64_e32 v[18:19], v[142:143]
	v_mov_b64_e32 v[20:21], v[144:145]
	v_mov_b64_e32 v[22:23], v[146:147]
	v_mov_b64_e32 v[24:25], v[148:149]
	v_mov_b64_e32 v[26:27], v[150:151]
	v_mov_b64_e32 v[28:29], v[152:153]
	v_mov_b64_e32 v[30:31], v[154:155]
	v_mov_b64_e32 v[32:33], v[156:157]
	v_mov_b64_e32 v[34:35], v[158:159]
	v_mov_b64_e32 v[36:37], v[160:161]
	v_mov_b64_e32 v[90:91], v[162:163]
	v_mov_b64_e32 v[92:93], v[164:165]
	v_mov_b64_e32 v[94:95], v[166:167]
	v_mov_b64_e32 v[96:97], v[168:169]
	v_mov_b64_e32 v[98:99], v[170:171]
	v_mov_b64_e32 v[100:101], v[172:173]
	v_mov_b64_e32 v[102:103], v[174:175]
	s_cmpk_lt_i32 s4, 0x4000
	s_cselect_b64 s[74:75], -1, 0
	s_and_b64 s[6:7], s[74:75], exec
	s_cselect_b32 s6, s90, 0xff
	s_and_b32 s5, s4, s6
	s_add_i32 s10, s4, s36
	s_cmpk_gt_i32 s10, 0x47ff
	s_cbranch_scc1 .Lf1_pf_done
	s_mul_i32 s11, s36, 0x1200
	s_mul_hi_i32 s13, s36, 0x1200
	s_add_u32 s12, s72, s11
	s_addc_u32 s13, s73, s13
	v_lshl_add_u64 v[176:177], s[12:13], 0, v[82:83]
	v_lshl_add_u64 v[178:179], s[12:13], 0, v[88:89]
	global_load_dwordx4 v[158:161], v[176:177], off offset:-2816
	global_load_dwordx4 v[142:145], v[176:177], off
	global_load_dwordx4 v[154:157], v[178:179], off offset:1024
	global_load_dwordx4 v[146:149], v[178:179], off offset:3840
	v_lshl_add_u64 v[180:181], s[12:13], 0, v[86:87]
	v_lshl_add_u64 v[182:183], s[12:13], 0, v[78:79]
	global_load_dwordx4 v[150:153], v[180:181], off
	global_load_dwordx2 v[164:165], v[182:183], off offset:1280
	global_load_dwordx2 v[166:167], v[182:183], off offset:2304
	global_load_dwordx2 v[162:163], v[182:183], off offset:1792
	s_cmpk_lt_i32 s10, 0x4000
	s_cselect_b32 s14, s90, 0xff
	s_and_b32 s11, s10, s14
	s_cmp_eq_u32 s11, 0
	s_cbranch_scc1 .Lf1l_prev_zero
	global_load_dwordx2 v[168:169], v[182:183], off offset:-3328
	global_load_dwordx2 v[170:171], v[182:183], off offset:-2304
	s_branch .Lf1l_prev_done

; __device__ __forceinline__ float dpp_x1(float v) { return __builtin_bit_cast(float, __builtin_amdgcn_update_dpp(0, __builtin_bit_cast(int, v), 0xB1, 0xF, 0xF, false)); }
; __device__ __forceinline__ float dpp_x2(float v) { return __builtin_bit_cast(float, __builtin_amdgcn_update_dpp(0, __builtin_bit_cast(int, v), 0x4E, 0xF, 0xF, false)); }
; __device__ __forceinline__ float dpp_hm(float v) { return __builtin_bit_cast(float, __builtin_amdgcn_update_dpp(0, __builtin_bit_cast(int, v), 0x141, 0xF, 0xF, false)); }
; __global__ void __launch_bounds__(512, 2) fwd_mega(Args args) {
;     ...
;                     { float v[8]; UNPK8(a8, v); float ss = 0.f;
; #pragma unroll
;                       for (int e = 0; e < 8; ++e) ss += v[e] * v[e];
;                       ss += dpp_x1(ss); ss += dpp_x2(ss); ss += dpp_hm(ss);
;                       const float rs = rsqrtf(ss * (1.0f / 64.0f) + EPS);
; #pragma unroll
;                       for (int e = 0; e < 8; ++e) v[e] = v[e] * rs * g8[e];
;                       if (lat) { const float posv = (lane & 7) < 4 ? prow : pcol;
; #pragma unroll
;                           for (int e = 0; e < 8; ++e) { const float ang = posv * inv8[e], c = __cosf(ang), sn = __sinf(ang); const float yp = dpp_x2(v[e]);
;                               v[e] = (lane & 2) ? v[e] * c + yp * sn : v[e] * c - yp * sn; } }
.Lf1l_next_done:
.Lf1_pf_done:
.LBB0_194:
	v_lshlrev_b32_e32 v108, 16, v34
	v_and_b32_e32 v109, 0xffff0000, v34
	v_pk_mul_f32 v[110:111], v[108:109], v[108:109]
	v_lshlrev_b32_e32 v128, 16, v35
	v_and_b32_e32 v129, 0xffff0000, v35
	v_pk_mul_f32 v[34:35], v[128:129], v[128:129]
	v_add_f32_e32 v110, v110, v111
	v_lshlrev_b32_e32 v130, 16, v36
	v_and_b32_e32 v131, 0xffff0000, v36
	v_add_f32_e32 v34, v110, v34
	v_lshlrev_b32_e32 v106, 16, v37
	v_and_b32_e32 v107, 0xffff0000, v37
	v_pk_mul_f32 v[36:37], v[130:131], v[130:131]
	v_add_f32_e32 v34, v34, v35
	v_add_f32_e32 v34, v34, v36
	v_pk_mul_f32 v[104:105], v[106:107], v[106:107]
	v_add_f32_e32 v34, v34, v37
	v_add_f32_e32 v34, v34, v104
	v_add_f32_e32 v34, v34, v105
	s_lshr_b32 s6, s5, 6
	v_cvt_f32_ubyte0_e32 v125, s6
	v_add_f32_dpp v34, v34, v34 quad_perm:[1,0,3,2] row_mask:0xf bank_mask:0xf bound_ctrl:1
	s_and_b32 s6, s4, 63
	v_cvt_f32_ubyte0_e32 v126, s6
	v_add_f32_dpp v34, v34, v34 quad_perm:[2,3,0,1] row_mask:0xf bank_mask:0xf bound_ctrl:1
	s_nop 1
	v_add_f32_dpp v34, v34, v34 row_half_mirror row_mask:0xf bank_mask:0xf bound_ctrl:1
	v_fmamk_f32 v34, v34, 0x3c800000, v192
	v_mul_f32_e32 v35, 0x4b800000, v34
	v_cmp_gt_f32_e32 vcc, s2, v34
	s_nop 1
	v_cndmask_b32_e32 v34, v34, v35, vcc
	v_rsq_f32_e32 v34, v34
	s_nop 0
	v_mul_f32_e32 v35, 0x45800000, v34
	v_cndmask_b32_e32 v110, v34, v35, vcc
	v_pk_mul_f32 v[34:35], v[110:111], v[108:109] op_sel_hi:[0,1]
	v_pk_mul_f32 v[36:37], v[110:111], v[128:129] op_sel_hi:[0,1]
	v_pk_mul_f32 v[104:105], v[110:111], v[130:131] op_sel_hi:[0,1]
	v_pk_mul_f32 v[106:107], v[110:111], v[106:107] op_sel_hi:[0,1]
	v_cndmask_b32_e64 v108, 0, 1, s[74:75]
	v_pk_mul_f32 v[34:35], v[34:35], v[72:73]
	v_pk_mul_f32 v[36:37], v[36:37], v[70:71]
	v_pk_mul_f32 v[104:105], v[104:105], v[68:69]
	v_cmp_ne_u32_e64 s[58:59], 1, v108
	s_andn2_b64 vcc, exec, s[74:75]
	v_pk_mul_f32 v[106:107], v[106:107], v[66:67]
	s_cbranch_vccnz .LBB0_196
	v_cndmask_b32_e64 v127, v126, v125, s[44:45]
	v_mul_f32_e32 v108, v127, v116
	v_mul_f32_e32 v109, 0.15915494, v108
	v_cos_f32_e32 v108, v109
	v_sin_f32_e32 v110, v109
	v_mul_f32_e32 v109, v127, v117
	v_mul_f32_e32 v109, 0.15915494, v109
	v_sin_f32_e32 v111, v109
	v_mov_b32_e32 v128, v1
	v_mov_b32_e32 v129, v1
	v_mov_b32_e32 v132, v1
	v_mov_b32_dpp v128, v34 quad_perm:[2,3,0,1] row_mask:0xf bank_mask:0xf
	v_mov_b32_dpp v129, v35 quad_perm:[2,3,0,1] row_mask:0xf bank_mask:0xf
	v_pk_mul_f32 v[110:111], v[110:111], v[128:129]
	v_mul_f32_e32 v128, v127, v115
	v_mul_f32_e32 v129, 0.15915494, v128
	v_cos_f32_e32 v128, v129
	v_sin_f32_e32 v130, v129
	v_mul_f32_e32 v129, v127, v114
	v_mul_f32_e32 v129, 0.15915494, v129
	v_sin_f32_e32 v131, v129
	v_mov_b32_e32 v133, v1
	v_mov_b32_dpp v132, v36 quad_perm:[2,3,0,1] row_mask:0xf bank_mask:0xf
	v_mov_b32_e32 v136, v1
	v_mov_b32_dpp v133, v37 quad_perm:[2,3,0,1] row_mask:0xf bank_mask:0xf
	v_pk_mul_f32 v[130:131], v[130:131], v[132:133]
	v_mul_f32_e32 v132, v127, v113
	v_mul_f32_e32 v133, 0.15915494, v132
	v_cos_f32_e32 v132, v133
	v_sin_f32_e32 v134, v133
	v_mul_f32_e32 v133, v127, v112
	v_mul_f32_e32 v133, 0.15915494, v133
	v_sin_f32_e32 v135, v133
	v_mov_b32_e32 v137, v1
	v_mov_b32_dpp v136, v104 quad_perm:[2,3,0,1] row_mask:0xf bank_mask:0xf
	v_cos_f32_e32 v109, v109
	v_mov_b32_dpp v137, v105 quad_perm:[2,3,0,1] row_mask:0xf bank_mask:0xf
	v_pk_mul_f32 v[134:135], v[134:135], v[136:137]
	v_mul_f32_e32 v136, v127, v75
	v_mul_f32_e32 v127, v127, v39
	v_mul_f32_e32 v137, 0.15915494, v136
	v_mul_f32_e32 v127, 0.15915494, v127
	v_sin_f32_e32 v138, v137
	v_sin_f32_e32 v139, v127
	v_cos_f32_e32 v129, v129
	v_cos_f32_e32 v133, v133
	v_cos_f32_e32 v136, v137
	v_mov_b32_e32 v140, v1
	v_cos_f32_e32 v137, v127
	v_mov_b32_e32 v141, v1
	v_mov_b32_dpp v140, v106 quad_perm:[2,3,0,1] row_mask:0xf bank_mask:0xf
	v_cndmask_b32_e64 v111, v111, -v111, s[46:47]
	v_mov_b32_dpp v141, v107 quad_perm:[2,3,0,1] row_mask:0xf bank_mask:0xf
	v_pk_mul_f32 v[138:139], v[138:139], v[140:141]
	v_cndmask_b32_e64 v110, v110, -v110, s[46:47]
	v_cndmask_b32_e64 v131, v131, -v131, s[46:47]
	v_cndmask_b32_e64 v130, v130, -v130, s[46:47]
	v_cndmask_b32_e64 v135, v135, -v135, s[46:47]
	v_cndmask_b32_e64 v134, v134, -v134, s[46:47]
	v_cndmask_b32_e64 v139, v139, -v139, s[46:47]
	v_cndmask_b32_e64 v138, v138, -v138, s[46:47]
	v_pk_fma_f32 v[106:107], v[106:107], v[136:137], v[138:139]
	v_pk_fma_f32 v[104:105], v[104:105], v[132:133], v[134:135]
	v_pk_fma_f32 v[36:37], v[36:37], v[128:129], v[130:131]
	v_pk_fma_f32 v[34:35], v[34:35], v[108:109], v[110:111]

; __device__ __forceinline__ unsigned cvt_pk_bf16(float lo, float hi) { unsigned r; asm volatile("v_cvt_pk_bf16_f32 %0, %1, %2" : "=v"(r) : "v"(lo), "v"(hi)); return r; }
; __device__ __forceinline__ float silu_f(float g) { return g * __builtin_amdgcn_rcpf(1.0f + __expf(-g)); }
;     __device__ __forceinline__ void operator()(const f32x4 (&acc)[2][2][4][2], const Unit& u, int wr, int wc, int fr, int fq) const {
;         const int row0 = u.pm * BM + wr * 64 + fr, col0 = u.pn * HALF + wc * 32 + 8 * fq;
; #pragma unroll
;         for (int ai = 0; ai < 2; ++ai)
; #pragma unroll
;             for (int m = 0; m < 4; ++m) {
;                 bf16_t* rowp = O + (size_t)(row0 + ai * HALF + m * 16) * DFF + col0;
;                 const f32x4 g0 = acc[ai][0][m][0], g1 = acc[ai][0][m][1], u0 = acc[ai][1][m][0], u1 = acc[ai][1][m][1];
;                 u32x4 w;
;                 w.x = cvt_pk_bf16(silu_f(g0[0]) * u0[0], silu_f(g0[1]) * u0[1]);
;                 w.y = cvt_pk_bf16(silu_f(g0[2]) * u0[2], silu_f(g0[3]) * u0[3]);
;                 w.z = cvt_pk_bf16(silu_f(g1[0]) * u1[0], silu_f(g1[1]) * u1[1]);
;                 w.w = cvt_pk_bf16(silu_f(g1[2]) * u1[2], silu_f(g1[3]) * u1[3]);
;                 *(u32x4*)rowp = w;
;             }
.LBB0_529:
	v_lshl_or_b32 v142, s53, 7, v146
	v_lshl_add_u32 v148, s52, 8, v144
	v_ashrrev_i32_e32 v143, 31, v142
	v_mov_b64_e32 v[140:141], s[38:39]
	v_lshlrev_b64 v[142:143], 1, v[142:143]
	s_andn2_b64 vcc, exec, s[40:41]
	v_mov_b32_e32 v160, 0xbfb8aa3b
	v_mad_i64_i32 v[150:151], s[52:53], v148, s79, v[140:141]
	v_pk_mul_f32 v[152:153], v[126:127], v[160:161] op_sel_hi:[1,0]
	v_pk_mul_f32 v[154:155], v[128:129], v[160:161] op_sel_hi:[1,0]
	v_pk_mul_f32 v[156:157], v[118:119], v[160:161] op_sel_hi:[1,0]
	v_pk_mul_f32 v[158:159], v[120:121], v[160:161] op_sel_hi:[1,0]
	v_lshl_add_u64 v[150:151], v[150:151], 0, v[142:143]
	v_exp_f32_e32 v152, v152
	v_exp_f32_e32 v153, v153
	v_exp_f32_e32 v154, v154
	v_exp_f32_e32 v155, v155
	v_exp_f32_e32 v156, v156
	v_exp_f32_e32 v157, v157
	v_exp_f32_e32 v158, v158
	v_exp_f32_e32 v159, v159
	v_pk_add_f32 v[152:153], v[152:153], 1.0 op_sel_hi:[1,0]
	v_pk_add_f32 v[154:155], v[154:155], 1.0 op_sel_hi:[1,0]
	v_pk_add_f32 v[156:157], v[156:157], 1.0 op_sel_hi:[1,0]
	v_pk_add_f32 v[158:159], v[158:159], 1.0 op_sel_hi:[1,0]
	v_rcp_f32_e32 v152, v152
	v_rcp_f32_e32 v153, v153
	v_rcp_f32_e32 v154, v154
	v_rcp_f32_e32 v155, v155
	v_rcp_f32_e32 v156, v156
	v_rcp_f32_e32 v157, v157
	v_rcp_f32_e32 v158, v158
	v_rcp_f32_e32 v159, v159
	v_pk_mul_f32 v[152:153], v[126:127], v[152:153]
	v_pk_mul_f32 v[154:155], v[128:129], v[154:155]
	v_pk_mul_f32 v[156:157], v[118:119], v[156:157]
	v_pk_mul_f32 v[158:159], v[120:121], v[158:159]
	v_pk_mul_f32 v[152:153], v[122:123], v[152:153]
	v_pk_mul_f32 v[154:155], v[124:125], v[154:155]
	v_pk_mul_f32 v[156:157], v[114:115], v[156:157]
	v_pk_mul_f32 v[158:159], v[116:117], v[158:159]
	v_cvt_pk_bf16_f32 v122, v152, v153
	v_cvt_pk_bf16_f32 v123, v154, v155
	v_cvt_pk_bf16_f32 v124, v156, v157
	v_cvt_pk_bf16_f32 v125, v158, v159
	flat_store_dwordx4 v[150:151], v[122:125]
	v_or_b32_e32 v149, 16, v148
	v_mad_i64_i32 v[162:163], s[52:53], v149, s79, v[140:141]
	v_pk_mul_f32 v[152:153], v[110:111], v[160:161] op_sel_hi:[1,0]
	v_pk_mul_f32 v[154:155], v[112:113], v[160:161] op_sel_hi:[1,0]
	v_pk_mul_f32 v[156:157], v[102:103], v[160:161] op_sel_hi:[1,0]
	v_pk_mul_f32 v[158:159], v[104:105], v[160:161] op_sel_hi:[1,0]
	v_lshl_add_u64 v[162:163], v[162:163], 0, v[142:143]
	v_exp_f32_e32 v152, v152
	v_exp_f32_e32 v153, v153
	v_exp_f32_e32 v154, v154
	v_exp_f32_e32 v155, v155
	v_exp_f32_e32 v156, v156
	v_exp_f32_e32 v157, v157
	v_exp_f32_e32 v158, v158
	v_exp_f32_e32 v159, v159
	v_pk_add_f32 v[152:153], v[152:153], 1.0 op_sel_hi:[1,0]
	v_pk_add_f32 v[154:155], v[154:155], 1.0 op_sel_hi:[1,0]
	v_pk_add_f32 v[156:157], v[156:157], 1.0 op_sel_hi:[1,0]
	v_pk_add_f32 v[158:159], v[158:159], 1.0 op_sel_hi:[1,0]
	v_rcp_f32_e32 v152, v152
	v_rcp_f32_e32 v153, v153
	v_rcp_f32_e32 v154, v154
	v_rcp_f32_e32 v155, v155
	v_rcp_f32_e32 v156, v156
	v_rcp_f32_e32 v157, v157
	v_rcp_f32_e32 v158, v158
	v_rcp_f32_e32 v159, v159
	v_pk_mul_f32 v[152:153], v[110:111], v[152:153]
	v_pk_mul_f32 v[154:155], v[112:113], v[154:155]
	v_pk_mul_f32 v[156:157], v[102:103], v[156:157]
	v_pk_mul_f32 v[158:159], v[104:105], v[158:159]
	v_pk_mul_f32 v[152:153], v[106:107], v[152:153]
	v_pk_mul_f32 v[154:155], v[108:109], v[154:155]
	v_pk_mul_f32 v[156:157], v[98:99], v[156:157]
	v_pk_mul_f32 v[158:159], v[100:101], v[158:159]
	v_cvt_pk_bf16_f32 v106, v152, v153
	v_cvt_pk_bf16_f32 v107, v154, v155
	v_cvt_pk_bf16_f32 v108, v156, v157
	v_cvt_pk_bf16_f32 v109, v158, v159
	flat_store_dwordx4 v[162:163], v[106:109]
	v_or_b32_e32 v149, 32, v148
	v_mad_i64_i32 v[150:151], s[52:53], v149, s79, v[140:141]
	v_pk_mul_f32 v[152:153], v[94:95], v[160:161] op_sel_hi:[1,0]
	v_pk_mul_f32 v[154:155], v[96:97], v[160:161] op_sel_hi:[1,0]
	v_pk_mul_f32 v[156:157], v[86:87], v[160:161] op_sel_hi:[1,0]
	v_pk_mul_f32 v[158:159], v[88:89], v[160:161] op_sel_hi:[1,0]
	v_lshl_add_u64 v[150:151], v[150:151], 0, v[142:143]
	v_exp_f32_e32 v152, v152
	v_exp_f32_e32 v153, v153
	v_exp_f32_e32 v154, v154
	v_exp_f32_e32 v155, v155
	v_exp_f32_e32 v156, v156
	v_exp_f32_e32 v157, v157
	v_exp_f32_e32 v158, v158
	v_exp_f32_e32 v159, v159
	v_pk_add_f32 v[152:153], v[152:153], 1.0 op_sel_hi:[1,0]
	v_pk_add_f32 v[154:155], v[154:155], 1.0 op_sel_hi:[1,0]
	v_pk_add_f32 v[156:157], v[156:157], 1.0 op_sel_hi:[1,0]
	v_pk_add_f32 v[158:159], v[158:159], 1.0 op_sel_hi:[1,0]
	v_rcp_f32_e32 v152, v152
	v_rcp_f32_e32 v153, v153
	v_rcp_f32_e32 v154, v154
	v_rcp_f32_e32 v155, v155
	v_rcp_f32_e32 v156, v156
	v_rcp_f32_e32 v157, v157
	v_rcp_f32_e32 v158, v158
	v_rcp_f32_e32 v159, v159
	v_pk_mul_f32 v[152:153], v[94:95], v[152:153]
	v_pk_mul_f32 v[154:155], v[96:97], v[154:155]
	v_pk_mul_f32 v[156:157], v[86:87], v[156:157]
	v_pk_mul_f32 v[158:159], v[88:89], v[158:159]
	v_pk_mul_f32 v[152:153], v[90:91], v[152:153]
	v_pk_mul_f32 v[154:155], v[92:93], v[154:155]
	v_pk_mul_f32 v[156:157], v[82:83], v[156:157]
	v_pk_mul_f32 v[158:159], v[84:85], v[158:159]
	v_cvt_pk_bf16_f32 v90, v152, v153
	v_cvt_pk_bf16_f32 v91, v154, v155
	v_cvt_pk_bf16_f32 v92, v156, v157
	v_cvt_pk_bf16_f32 v93, v158, v159
	flat_store_dwordx4 v[150:151], v[90:93]
	v_or_b32_e32 v149, 48, v148
	v_mad_i64_i32 v[162:163], s[52:53], v149, s79, v[140:141]
	v_pk_mul_f32 v[152:153], v[78:79], v[160:161] op_sel_hi:[1,0]
	v_pk_mul_f32 v[154:155], v[80:81], v[160:161] op_sel_hi:[1,0]
	v_pk_mul_f32 v[156:157], v[70:71], v[160:161] op_sel_hi:[1,0]
	v_pk_mul_f32 v[158:159], v[72:73], v[160:161] op_sel_hi:[1,0]
	v_lshl_add_u64 v[162:163], v[162:163], 0, v[142:143]
	v_exp_f32_e32 v152, v152
	v_exp_f32_e32 v153, v153
	v_exp_f32_e32 v154, v154
	v_exp_f32_e32 v155, v155
	v_exp_f32_e32 v156, v156
	v_exp_f32_e32 v157, v157
; __device__ __forceinline__ unsigned cvt_pk_bf16(float lo, float hi) { unsigned r; asm volatile("v_cvt_pk_bf16_f32 %0, %1, %2" : "=v"(r) : "v"(lo), "v"(hi)); return r; }
; __device__ __forceinline__ float silu_f(float g) { return g * __builtin_amdgcn_rcpf(1.0f + __expf(-g)); }
;     __device__ __forceinline__ void operator()(const f32x4 (&acc)[2][2][4][2], const Unit& u, int wr, int wc, int fr, int fq) const {
;     ...
;         for (int ai = 0; ai < 2; ++ai)
; #pragma unroll
;             for (int m = 0; m < 4; ++m) {
;                 bf16_t* rowp = O + (size_t)(row0 + ai * HALF + m * 16) * DFF + col0;
;                 const f32x4 g0 = acc[ai][0][m][0], g1 = acc[ai][0][m][1], u0 = acc[ai][1][m][0], u1 = acc[ai][1][m][1];
;                 u32x4 w;
;                 w.x = cvt_pk_bf16(silu_f(g0[0]) * u0[0], silu_f(g0[1]) * u0[1]);
;                 w.y = cvt_pk_bf16(silu_f(g0[2]) * u0[2], silu_f(g0[3]) * u0[3]);
;                 w.z = cvt_pk_bf16(silu_f(g1[0]) * u1[0], silu_f(g1[1]) * u1[1]);
;                 w.w = cvt_pk_bf16(silu_f(g1[2]) * u1[2], silu_f(g1[3]) * u1[3]);
;                 *(u32x4*)rowp = w;
;             }
	v_exp_f32_e32 v158, v158
	v_exp_f32_e32 v159, v159
	v_pk_add_f32 v[152:153], v[152:153], 1.0 op_sel_hi:[1,0]
	v_pk_add_f32 v[154:155], v[154:155], 1.0 op_sel_hi:[1,0]
	v_pk_add_f32 v[156:157], v[156:157], 1.0 op_sel_hi:[1,0]
	v_pk_add_f32 v[158:159], v[158:159], 1.0 op_sel_hi:[1,0]
	v_rcp_f32_e32 v152, v152
	v_rcp_f32_e32 v153, v153
	v_rcp_f32_e32 v154, v154
	v_rcp_f32_e32 v155, v155
	v_rcp_f32_e32 v156, v156
	v_rcp_f32_e32 v157, v157
	v_rcp_f32_e32 v158, v158
	v_rcp_f32_e32 v159, v159
	v_pk_mul_f32 v[152:153], v[78:79], v[152:153]
	v_pk_mul_f32 v[154:155], v[80:81], v[154:155]
	v_pk_mul_f32 v[156:157], v[70:71], v[156:157]
	v_pk_mul_f32 v[158:159], v[72:73], v[158:159]
	v_pk_mul_f32 v[152:153], v[74:75], v[152:153]
	v_pk_mul_f32 v[154:155], v[76:77], v[154:155]
	v_pk_mul_f32 v[156:157], v[66:67], v[156:157]
	v_pk_mul_f32 v[158:159], v[68:69], v[158:159]
	v_cvt_pk_bf16_f32 v74, v152, v153
	v_cvt_pk_bf16_f32 v75, v154, v155
	v_cvt_pk_bf16_f32 v76, v156, v157
	v_cvt_pk_bf16_f32 v77, v158, v159
	flat_store_dwordx4 v[162:163], v[74:77]
	v_add_u32_e32 v149, 0x80, v148
	v_mad_i64_i32 v[150:151], s[52:53], v149, s79, v[140:141]
	v_pk_mul_f32 v[152:153], v[62:63], v[160:161] op_sel_hi:[1,0]
	v_pk_mul_f32 v[154:155], v[64:65], v[160:161] op_sel_hi:[1,0]
	v_pk_mul_f32 v[156:157], v[54:55], v[160:161] op_sel_hi:[1,0]
	v_pk_mul_f32 v[158:159], v[56:57], v[160:161] op_sel_hi:[1,0]
	v_lshl_add_u64 v[150:151], v[150:151], 0, v[142:143]
	v_exp_f32_e32 v152, v152
	v_exp_f32_e32 v153, v153
	v_exp_f32_e32 v154, v154
	v_exp_f32_e32 v155, v155
	v_exp_f32_e32 v156, v156
	v_exp_f32_e32 v157, v157
	v_exp_f32_e32 v158, v158
	v_exp_f32_e32 v159, v159
	v_pk_add_f32 v[152:153], v[152:153], 1.0 op_sel_hi:[1,0]
	v_pk_add_f32 v[154:155], v[154:155], 1.0 op_sel_hi:[1,0]
	v_pk_add_f32 v[156:157], v[156:157], 1.0 op_sel_hi:[1,0]
	v_pk_add_f32 v[158:159], v[158:159], 1.0 op_sel_hi:[1,0]
	v_rcp_f32_e32 v152, v152
	v_rcp_f32_e32 v153, v153
	v_rcp_f32_e32 v154, v154
	v_rcp_f32_e32 v155, v155
	v_rcp_f32_e32 v156, v156
	v_rcp_f32_e32 v157, v157
	v_rcp_f32_e32 v158, v158
	v_rcp_f32_e32 v159, v159
	v_pk_mul_f32 v[152:153], v[62:63], v[152:153]
	v_pk_mul_f32 v[154:155], v[64:65], v[154:155]
	v_pk_mul_f32 v[156:157], v[54:55], v[156:157]
	v_pk_mul_f32 v[158:159], v[56:57], v[158:159]
	v_pk_mul_f32 v[152:153], v[58:59], v[152:153]
	v_pk_mul_f32 v[154:155], v[60:61], v[154:155]
	v_pk_mul_f32 v[156:157], v[50:51], v[156:157]
	v_pk_mul_f32 v[158:159], v[52:53], v[158:159]
	v_cvt_pk_bf16_f32 v58, v152, v153
	v_cvt_pk_bf16_f32 v59, v154, v155
	v_cvt_pk_bf16_f32 v60, v156, v157
	v_cvt_pk_bf16_f32 v61, v158, v159
	flat_store_dwordx4 v[150:151], v[58:61]
	v_add_u32_e32 v149, 0x90, v148
	v_mad_i64_i32 v[162:163], s[52:53], v149, s79, v[140:141]
	v_pk_mul_f32 v[152:153], v[46:47], v[160:161] op_sel_hi:[1,0]
	v_pk_mul_f32 v[154:155], v[48:49], v[160:161] op_sel_hi:[1,0]
	v_pk_mul_f32 v[156:157], v[38:39], v[160:161] op_sel_hi:[1,0]
	v_pk_mul_f32 v[158:159], v[40:41], v[160:161] op_sel_hi:[1,0]
	v_lshl_add_u64 v[162:163], v[162:163], 0, v[142:143]
	v_exp_f32_e32 v152, v152
	v_exp_f32_e32 v153, v153
	v_exp_f32_e32 v154, v154
	v_exp_f32_e32 v155, v155
	v_exp_f32_e32 v156, v156
	v_exp_f32_e32 v157, v157
	v_exp_f32_e32 v158, v158
	v_exp_f32_e32 v159, v159
	v_pk_add_f32 v[152:153], v[152:153], 1.0 op_sel_hi:[1,0]
	v_pk_add_f32 v[154:155], v[154:155], 1.0 op_sel_hi:[1,0]
	v_pk_add_f32 v[156:157], v[156:157], 1.0 op_sel_hi:[1,0]
	v_pk_add_f32 v[158:159], v[158:159], 1.0 op_sel_hi:[1,0]
	v_rcp_f32_e32 v152, v152
	v_rcp_f32_e32 v153, v153
	v_rcp_f32_e32 v154, v154
	v_rcp_f32_e32 v155, v155
	v_rcp_f32_e32 v156, v156
	v_rcp_f32_e32 v157, v157
	v_rcp_f32_e32 v158, v158
	v_rcp_f32_e32 v159, v159
	v_pk_mul_f32 v[152:153], v[46:47], v[152:153]
	v_pk_mul_f32 v[154:155], v[48:49], v[154:155]
; __device__ __forceinline__ unsigned cvt_pk_bf16(float lo, float hi) { unsigned r; asm volatile("v_cvt_pk_bf16_f32 %0, %1, %2" : "=v"(r) : "v"(lo), "v"(hi)); return r; }
; __device__ __forceinline__ float silu_f(float g) { return g * __builtin_amdgcn_rcpf(1.0f + __expf(-g)); }
;     __device__ __forceinline__ void operator()(const f32x4 (&acc)[2][2][4][2], const Unit& u, int wr, int wc, int fr, int fq) const {
;     ...
;         for (int ai = 0; ai < 2; ++ai)
; #pragma unroll
;             for (int m = 0; m < 4; ++m) {
;                 bf16_t* rowp = O + (size_t)(row0 + ai * HALF + m * 16) * DFF + col0;
;                 const f32x4 g0 = acc[ai][0][m][0], g1 = acc[ai][0][m][1], u0 = acc[ai][1][m][0], u1 = acc[ai][1][m][1];
;                 u32x4 w;
;                 w.x = cvt_pk_bf16(silu_f(g0[0]) * u0[0], silu_f(g0[1]) * u0[1]);
;                 w.y = cvt_pk_bf16(silu_f(g0[2]) * u0[2], silu_f(g0[3]) * u0[3]);
;                 w.z = cvt_pk_bf16(silu_f(g1[0]) * u1[0], silu_f(g1[1]) * u1[1]);
;                 w.w = cvt_pk_bf16(silu_f(g1[2]) * u1[2], silu_f(g1[3]) * u1[3]);
;                 *(u32x4*)rowp = w;
;             }
	v_pk_mul_f32 v[156:157], v[38:39], v[156:157]
	v_pk_mul_f32 v[158:159], v[40:41], v[158:159]
	v_pk_mul_f32 v[152:153], v[42:43], v[152:153]
	v_pk_mul_f32 v[154:155], v[44:45], v[154:155]
	v_pk_mul_f32 v[156:157], v[34:35], v[156:157]
	v_pk_mul_f32 v[158:159], v[36:37], v[158:159]
	v_cvt_pk_bf16_f32 v42, v152, v153
	v_cvt_pk_bf16_f32 v43, v154, v155
	v_cvt_pk_bf16_f32 v44, v156, v157
	v_cvt_pk_bf16_f32 v45, v158, v159
	flat_store_dwordx4 v[162:163], v[42:45]
	v_add_u32_e32 v149, 0xa0, v148
	v_mad_i64_i32 v[150:151], s[52:53], v149, s79, v[140:141]
	v_pk_mul_f32 v[152:153], v[30:31], v[160:161] op_sel_hi:[1,0]
	v_pk_mul_f32 v[154:155], v[32:33], v[160:161] op_sel_hi:[1,0]
	v_pk_mul_f32 v[156:157], v[22:23], v[160:161] op_sel_hi:[1,0]
	v_pk_mul_f32 v[158:159], v[24:25], v[160:161] op_sel_hi:[1,0]
	v_lshl_add_u64 v[150:151], v[150:151], 0, v[142:143]
	v_exp_f32_e32 v152, v152
	v_exp_f32_e32 v153, v153
	v_exp_f32_e32 v154, v154
	v_exp_f32_e32 v155, v155
	v_exp_f32_e32 v156, v156
	v_exp_f32_e32 v157, v157
	v_exp_f32_e32 v158, v158
	v_exp_f32_e32 v159, v159
	v_pk_add_f32 v[152:153], v[152:153], 1.0 op_sel_hi:[1,0]
	v_pk_add_f32 v[154:155], v[154:155], 1.0 op_sel_hi:[1,0]
	v_pk_add_f32 v[156:157], v[156:157], 1.0 op_sel_hi:[1,0]
	v_pk_add_f32 v[158:159], v[158:159], 1.0 op_sel_hi:[1,0]
	v_rcp_f32_e32 v152, v152
	v_rcp_f32_e32 v153, v153
	v_rcp_f32_e32 v154, v154
	v_rcp_f32_e32 v155, v155
	v_rcp_f32_e32 v156, v156
	v_rcp_f32_e32 v157, v157
	v_rcp_f32_e32 v158, v158
	v_rcp_f32_e32 v159, v159
	v_pk_mul_f32 v[152:153], v[30:31], v[152:153]
	v_pk_mul_f32 v[154:155], v[32:33], v[154:155]
	v_pk_mul_f32 v[156:157], v[22:23], v[156:157]
	v_pk_mul_f32 v[158:159], v[24:25], v[158:159]
	v_pk_mul_f32 v[152:153], v[26:27], v[152:153]
	v_pk_mul_f32 v[154:155], v[28:29], v[154:155]
	v_pk_mul_f32 v[156:157], v[18:19], v[156:157]
	v_pk_mul_f32 v[158:159], v[20:21], v[158:159]
	v_cvt_pk_bf16_f32 v26, v152, v153
	v_cvt_pk_bf16_f32 v27, v154, v155
	v_cvt_pk_bf16_f32 v28, v156, v157
	v_cvt_pk_bf16_f32 v29, v158, v159
	flat_store_dwordx4 v[150:151], v[26:29]
	v_add_u32_e32 v149, 0xb0, v148
	v_mad_i64_i32 v[162:163], s[52:53], v149, s79, v[140:141]
	v_pk_mul_f32 v[152:153], v[14:15], v[160:161] op_sel_hi:[1,0]
	v_pk_mul_f32 v[154:155], v[16:17], v[160:161] op_sel_hi:[1,0]
	v_pk_mul_f32 v[156:157], v[6:7], v[160:161] op_sel_hi:[1,0]
	v_pk_mul_f32 v[158:159], v[8:9], v[160:161] op_sel_hi:[1,0]
	v_lshl_add_u64 v[162:163], v[162:163], 0, v[142:143]
	v_exp_f32_e32 v152, v152
	v_exp_f32_e32 v153, v153
	v_exp_f32_e32 v154, v154
	v_exp_f32_e32 v155, v155
	v_exp_f32_e32 v156, v156
	v_exp_f32_e32 v157, v157
	v_exp_f32_e32 v158, v158
	v_exp_f32_e32 v159, v159
	v_pk_add_f32 v[152:153], v[152:153], 1.0 op_sel_hi:[1,0]
	v_pk_add_f32 v[154:155], v[154:155], 1.0 op_sel_hi:[1,0]
	v_pk_add_f32 v[156:157], v[156:157], 1.0 op_sel_hi:[1,0]
	v_pk_add_f32 v[158:159], v[158:159], 1.0 op_sel_hi:[1,0]
	v_rcp_f32_e32 v152, v152
	v_rcp_f32_e32 v153, v153
	v_rcp_f32_e32 v154, v154
	v_rcp_f32_e32 v155, v155
	v_rcp_f32_e32 v156, v156
	v_rcp_f32_e32 v157, v157
	v_rcp_f32_e32 v158, v158
	v_rcp_f32_e32 v159, v159
	v_pk_mul_f32 v[152:153], v[14:15], v[152:153]
	v_pk_mul_f32 v[154:155], v[16:17], v[154:155]
	v_pk_mul_f32 v[156:157], v[6:7], v[156:157]
	v_pk_mul_f32 v[158:159], v[8:9], v[158:159]
	v_pk_mul_f32 v[152:153], v[10:11], v[152:153]
	v_pk_mul_f32 v[154:155], v[12:13], v[154:155]
	v_pk_mul_f32 v[156:157], v[2:3], v[156:157]
	v_pk_mul_f32 v[158:159], v[4:5], v[158:159]
	v_cvt_pk_bf16_f32 v10, v152, v153
	v_cvt_pk_bf16_f32 v11, v154, v155
	v_cvt_pk_bf16_f32 v12, v156, v157
	v_cvt_pk_bf16_f32 v13, v158, v159
	flat_store_dwordx4 v[162:163], v[10:13]
	s_mov_b64 s[52:53], -1
	s_cbranch_vccnz .LBB0_522
	s_andn2_b64 vcc, exec, s[22:23]
	s_cbranch_vccnz .LBB0_521
	s_barrier
	s_branch .LBB0_521
